# v3: FF1 epilogue norm2 statistics loaded for all 8 rows at once (one quad per lane + permlane reduction) instead of 8 serialized round trips
# speedup vs baseline: 1.0351x; 1.0144x over previous
.LBB0_1109:
	s_lshl_b32 s25, s8, 9
	s_and_b32 s25, s25, 0xfffff000
	s_lshl_b32 s7, s8, 8
	s_addk_i32 s25, 0xd000
	s_cmp_gt_i32 s8, 31
	s_cselect_b32 s8, s25, 0
	s_lshl_b64 s[36:37], s[8:9], 2
	s_add_u32 s36, s52, s36
	v_mov_b32_e32 v128, v175
	v_mov_b32_e32 v144, v171
	s_addc_u32 s37, s53, s37
	s_lshl_b32 s6, s6, 8
	s_add_i32 s7, s7, s54
	s_or_b32 s6, s6, s55
	v_add_u32_e32 v178, s7, v144
	v_lshl_add_u32 v168, v128, 3, s6
	v_ashrrev_i32_e32 v179, 31, v178
	v_ashrrev_i32_e32 v169, 31, v168
	v_lshlrev_b64 v[144:145], 6, v[178:179]
	v_lshl_add_u64 v[132:133], v[168:169], 2, s[36:37]
	v_lshl_add_u64 v[172:173], s[12:13], 0, v[144:145]
	global_load_dwordx4 v[136:139], v[132:133], off offset:16
	global_load_dwordx4 v[140:143], v[132:133], off
	global_load_dwordx4 v[128:131], v[132:133], off offset:528
	s_nop 0
	global_load_dwordx4 v[132:135], v[132:133], off offset:512
	s_nop 0
	v_lshlrev_b32_e32 v212, 4, v175
	v_mov_b32_e32 v213, 0
	v_lshl_add_u64 v[212:213], v[212:213], 0, v[172:173]
	s_mov_b64 s[6:7], 0x2000
	v_mov_b32_e32 v248, s22
	v_lshl_add_u64 v[250:251], v[212:213], 0, s[6:7]
	global_load_dwordx4 v[214:217], v[212:213], off
	global_load_dwordx4 v[218:221], v[212:213], off offset:1024
	global_load_dwordx4 v[222:225], v[212:213], off offset:2048
	global_load_dwordx4 v[226:229], v[212:213], off offset:3072
	global_load_dwordx4 v[230:233], v[250:251], off
	global_load_dwordx4 v[236:239], v[250:251], off offset:1024
	global_load_dwordx4 v[240:243], v[250:251], off offset:2048
	global_load_dwordx4 v[244:247], v[250:251], off offset:3072
	s_waitcnt vmcnt(0)
	v_add_f32_e32 v214, v214, v215
	v_add_f32_e32 v218, v218, v219
	v_add_f32_e32 v222, v222, v223
	v_add_f32_e32 v226, v226, v227
	v_add_f32_e32 v230, v230, v231
	v_add_f32_e32 v236, v236, v237
	v_add_f32_e32 v240, v240, v241
	v_add_f32_e32 v244, v244, v245
	v_add_f32_e32 v216, v216, v217
	v_add_f32_e32 v220, v220, v221
	v_add_f32_e32 v224, v224, v225
	v_add_f32_e32 v228, v228, v229
	v_add_f32_e32 v232, v232, v233
	v_add_f32_e32 v238, v238, v239
	v_add_f32_e32 v242, v242, v243
	v_add_f32_e32 v246, v246, v247
	v_add_f32_e32 v214, v214, v216
	v_add_f32_e32 v218, v218, v220
	v_add_f32_e32 v222, v222, v224
	v_add_f32_e32 v226, v226, v228
	v_add_f32_e32 v230, v230, v232
	v_add_f32_e32 v236, v236, v238
	v_add_f32_e32 v240, v240, v242
	v_add_f32_e32 v244, v244, v246
	v_mov_b32_e32 v215, v214
	v_mov_b32_e32 v219, v218
	v_mov_b32_e32 v223, v222
	v_mov_b32_e32 v227, v226
	v_mov_b32_e32 v231, v230
	v_mov_b32_e32 v237, v236
	v_mov_b32_e32 v241, v240
	v_mov_b32_e32 v245, v244
	v_permlane16_swap_b32_e32 v214, v215
	v_permlane16_swap_b32_e32 v218, v219
	v_permlane16_swap_b32_e32 v222, v223
	v_permlane16_swap_b32_e32 v226, v227
	v_permlane16_swap_b32_e32 v230, v231
	v_permlane16_swap_b32_e32 v236, v237
	v_permlane16_swap_b32_e32 v240, v241
	v_permlane16_swap_b32_e32 v244, v245
	v_add_f32_e32 v214, v214, v215
	v_add_f32_e32 v218, v218, v219
	v_add_f32_e32 v222, v222, v223
	v_add_f32_e32 v226, v226, v227
	v_add_f32_e32 v230, v230, v231
	v_add_f32_e32 v236, v236, v237
	v_add_f32_e32 v240, v240, v241
	v_add_f32_e32 v244, v244, v245
	v_mov_b32_e32 v215, v214
	v_mov_b32_e32 v219, v218
	v_mov_b32_e32 v223, v222
	v_mov_b32_e32 v227, v226
	v_mov_b32_e32 v231, v230
	v_mov_b32_e32 v237, v236
	v_mov_b32_e32 v241, v240
	v_mov_b32_e32 v245, v244
	v_permlane32_swap_b32_e32 v214, v215
	v_permlane32_swap_b32_e32 v218, v219
	v_permlane32_swap_b32_e32 v222, v223
	v_permlane32_swap_b32_e32 v226, v227
	v_permlane32_swap_b32_e32 v230, v231
	v_permlane32_swap_b32_e32 v236, v237
	v_permlane32_swap_b32_e32 v240, v241
	v_permlane32_swap_b32_e32 v244, v245
	v_add_f32_e32 v214, v214, v215
	v_add_f32_e32 v218, v218, v219
	v_add_f32_e32 v222, v222, v223
	v_add_f32_e32 v226, v226, v227
	v_add_f32_e32 v230, v230, v231
	v_add_f32_e32 v236, v236, v237
	v_add_f32_e32 v240, v240, v241
	v_add_f32_e32 v244, v244, v245
	v_fma_f32 v214, v214, s20, v248
	v_fma_f32 v218, v218, s20, v248
	v_fma_f32 v222, v222, s20, v248
	v_fma_f32 v226, v226, s20, v248
	v_fma_f32 v230, v230, s20, v248
	v_fma_f32 v236, v236, s20, v248
	v_fma_f32 v240, v240, s20, v248
	v_fma_f32 v244, v244, s20, v248
	v_rsq_f32_e32 v214, v214
	v_rsq_f32_e32 v218, v218
	v_rsq_f32_e32 v222, v222
	v_rsq_f32_e32 v226, v226
	v_rsq_f32_e32 v230, v230
	v_rsq_f32_e32 v236, v236
	v_rsq_f32_e32 v240, v240
	v_rsq_f32_e32 v244, v244
	v_pk_add_f32 v[146:147], v[146:147], v[150:151]
	v_pk_add_f32 v[144:145], v[144:145], v[148:149]
	v_pk_add_f32 v[172:173], v[192:193], v[198:199]
	v_pk_add_f32 v[176:177], v[190:191], v[196:197]
	v_pk_add_f32 v[180:181], v[172:173], v[146:147]
	v_add_u32_e32 v172, 16, v178
	v_ashrrev_i32_e32 v173, 31, v172
	v_pk_add_f32 v[176:177], v[176:177], v[144:145]
	v_lshlrev_b64 v[144:145], 6, v[172:173]
	v_lshl_add_u64 v[186:187], s[12:13], 0, v[144:145]
	v_pk_add_f32 v[144:145], v[144:145], v[148:149]
	v_pk_add_f32 v[146:147], v[146:147], v[150:151]
	v_pk_add_f32 v[190:191], v[190:191], v[196:197]
	v_pk_add_f32 v[186:187], v[192:193], v[198:199]
	v_pk_add_f32 v[144:145], v[190:191], v[144:145]
	v_pk_add_f32 v[146:147], v[186:187], v[146:147]
	v_mov_b32_e32 v148, v144
	v_mov_b32_e32 v149, v176
	v_mov_b32_e32 v176, v145
	v_pk_add_f32 v[144:145], v[148:149], v[176:177]
	v_mov_b32_e32 v148, v146
	v_mov_b32_e32 v149, v180
	v_pk_add_f32 v[144:145], v[148:149], v[144:145]
	v_mov_b32_e32 v180, v147
	v_pk_add_f32 v[144:145], v[180:181], v[144:145]
	v_mov_b64_e32 v[192:193], s[22:23]
	v_pk_fma_f32 v[144:145], v[144:145], s[20:21], v[192:193] op_sel_hi:[1,0,0]
	v_add_u32_e32 v180, 32, v178
	v_mul_f32_e32 v146, 0x4b800000, v145
	v_cmp_gt_f32_e64 s[6:7], s68, v145
	v_cmp_gt_f32_e32 vcc, s68, v144
	v_ashrrev_i32_e32 v181, 31, v180
	v_cndmask_b32_e64 v145, v145, v146, s[6:7]
	v_rsq_f32_e32 v145, v145
	s_nop 0
	v_mul_f32_e32 v146, 0x45800000, v145
	v_cndmask_b32_e64 v182, v145, v146, s[6:7]
	v_mov_b32_e32 v182, v214
	v_mul_f32_e32 v145, 0x4b800000, v144
	v_cndmask_b32_e32 v144, v144, v145, vcc
	v_rsq_f32_e32 v144, v144
	v_pk_fma_f32 v[126:127], v[126:127], v[182:183], v[142:143] op_sel_hi:[1,0,1]
	v_pk_fma_f32 v[124:125], v[124:125], v[182:183], v[140:141] op_sel_hi:[1,0,1]
	v_pk_fma_f32 v[120:121], v[120:121], v[182:183], v[136:137] op_sel_hi:[1,0,1]
	v_mul_f32_e32 v145, 0x45800000, v144
	v_cndmask_b32_e32 v170, v144, v145, vcc
	v_mov_b32_e32 v170, v218
	v_lshlrev_b64 v[144:145], 6, v[180:181]
	v_lshl_add_u64 v[176:177], s[12:13], 0, v[144:145]
	v_pk_fma_f32 v[122:123], v[122:123], v[182:183], v[138:139] op_sel_hi:[1,0,1]
	v_max_f32_e32 v124, 0, v124
	v_max_f32_e32 v120, 0, v120
	v_max_f32_e32 v125, 0, v125
	v_max_f32_e32 v121, 0, v121
	v_max_f32_e32 v126, 0, v126
	v_max_f32_e32 v127, 0, v127
	v_pk_mul_f32 v[124:125], v[124:125], v[124:125]
	v_pk_mul_f32 v[120:121], v[120:121], v[120:121]
	v_max_f32_e32 v122, 0, v122
	v_max_f32_e32 v123, 0, v123
	v_pk_mul_f32 v[126:127], v[126:127], v[126:127]
	v_pk_fma_f32 v[112:113], v[112:113], v[182:183], v[128:129] op_sel_hi:[1,0,1]
	v_pk_fma_f32 v[118:119], v[118:119], v[182:183], v[134:135] op_sel_hi:[1,0,1]
	v_pk_fma_f32 v[116:117], v[116:117], v[182:183], v[132:133] op_sel_hi:[1,0,1]
	v_pk_fma_f32 v[114:115], v[114:115], v[182:183], v[130:131] op_sel_hi:[1,0,1]
	v_max_f32_e32 v112, 0, v112
	v_max_f32_e32 v113, 0, v113
	v_max_f32_e32 v116, 0, v116
	v_max_f32_e32 v117, 0, v117
	v_max_f32_e32 v114, 0, v114
	v_max_f32_e32 v115, 0, v115
	v_pk_mul_f32 v[116:117], v[116:117], v[116:117]
	v_pk_fma_f32 v[108:109], v[108:109], v[170:171], v[140:141] op_sel_hi:[1,0,1]
	v_pk_fma_f32 v[104:105], v[104:105], v[170:171], v[136:137] op_sel_hi:[1,0,1]
	v_pk_fma_f32 v[110:111], v[110:111], v[170:171], v[142:143] op_sel_hi:[1,0,1]
	v_pk_fma_f32 v[106:107], v[106:107], v[170:171], v[138:139] op_sel_hi:[1,0,1]
	v_max_f32_e32 v108, 0, v108
	v_max_f32_e32 v104, 0, v104
	v_max_f32_e32 v109, 0, v109
	v_max_f32_e32 v105, 0, v105
	v_pk_mul_f32 v[108:109], v[108:109], v[108:109]
	v_max_f32_e32 v106, 0, v106
	v_max_f32_e32 v107, 0, v107
	v_pk_fma_f32 v[96:97], v[96:97], v[170:171], v[128:129] op_sel_hi:[1,0,1]
	v_pk_fma_f32 v[102:103], v[102:103], v[170:171], v[134:135] op_sel_hi:[1,0,1]
	v_pk_fma_f32 v[100:101], v[100:101], v[170:171], v[132:133] op_sel_hi:[1,0,1]
	v_pk_fma_f32 v[98:99], v[98:99], v[170:171], v[130:131] op_sel_hi:[1,0,1]
	v_max_f32_e32 v96, 0, v96
	v_max_f32_e32 v97, 0, v97
	v_max_f32_e32 v100, 0, v100
	v_max_f32_e32 v101, 0, v101
	v_max_f32_e32 v98, 0, v98
	v_max_f32_e32 v99, 0, v99
	v_pk_mul_f32 v[100:101], v[100:101], v[100:101]
	v_pk_add_f32 v[146:147], v[146:147], v[150:151]
	v_pk_add_f32 v[144:145], v[144:145], v[148:149]
	v_pk_add_f32 v[176:177], v[198:199], v[202:203]
	v_pk_add_f32 v[186:187], v[196:197], v[200:201]
	v_pk_add_f32 v[190:191], v[176:177], v[146:147]
	v_add_u32_e32 v176, 48, v178
	v_ashrrev_i32_e32 v177, 31, v176
	v_pk_add_f32 v[186:187], v[186:187], v[144:145]
	v_lshlrev_b64 v[144:145], 6, v[176:177]
	v_lshl_add_u64 v[200:201], s[12:13], 0, v[144:145]
	s_nop 0
	v_pk_add_f32 v[144:145], v[144:145], v[148:149]
	v_pk_add_f32 v[146:147], v[146:147], v[150:151]
	v_pk_add_f32 v[196:197], v[196:197], v[200:201]
	v_pk_add_f32 v[198:199], v[198:199], v[202:203]
	v_pk_add_f32 v[144:145], v[196:197], v[144:145]
	v_pk_add_f32 v[146:147], v[198:199], v[146:147]
	v_mov_b32_e32 v148, v144
	v_mov_b32_e32 v149, v186
	v_mov_b32_e32 v186, v145
	v_pk_add_f32 v[144:145], v[148:149], v[186:187]
	v_mov_b32_e32 v148, v146
	v_mov_b32_e32 v149, v190
	v_pk_add_f32 v[144:145], v[148:149], v[144:145]
	v_mov_b32_e32 v190, v147
	v_pk_add_f32 v[144:145], v[190:191], v[144:145]
	v_add_u32_e32 v190, 0x80, v178
	v_pk_fma_f32 v[144:145], v[144:145], s[20:21], v[192:193] op_sel_hi:[1,0,0]
	v_ashrrev_i32_e32 v191, 31, v190
	v_mul_f32_e32 v146, 0x4b800000, v145
	v_cmp_gt_f32_e64 s[6:7], s68, v145
	v_cmp_gt_f32_e32 vcc, s68, v144
	s_nop 0
	v_cndmask_b32_e64 v145, v145, v146, s[6:7]
	v_rsq_f32_e32 v145, v145
	s_nop 0
	v_mul_f32_e32 v146, 0x45800000, v145
	v_cndmask_b32_e64 v188, v145, v146, s[6:7]
	v_mov_b32_e32 v188, v222
	v_mul_f32_e32 v145, 0x4b800000, v144
	v_cndmask_b32_e32 v144, v144, v145, vcc
	v_rsq_f32_e32 v144, v144
	v_pk_fma_f32 v[92:93], v[92:93], v[188:189], v[140:141] op_sel_hi:[1,0,1]
	v_pk_fma_f32 v[88:89], v[88:89], v[188:189], v[136:137] op_sel_hi:[1,0,1]
	v_pk_fma_f32 v[94:95], v[94:95], v[188:189], v[142:143] op_sel_hi:[1,0,1]
	v_mul_f32_e32 v145, 0x45800000, v144
	v_cndmask_b32_e32 v174, v144, v145, vcc
	v_mov_b32_e32 v174, v226
	v_lshlrev_b64 v[144:145], 6, v[190:191]
	v_lshl_add_u64 v[186:187], s[12:13], 0, v[144:145]
	v_pk_fma_f32 v[90:91], v[90:91], v[188:189], v[138:139] op_sel_hi:[1,0,1]
	v_max_f32_e32 v92, 0, v92
	v_max_f32_e32 v88, 0, v88
	v_max_f32_e32 v93, 0, v93
	v_max_f32_e32 v89, 0, v89
	v_pk_mul_f32 v[92:93], v[92:93], v[92:93]
	v_max_f32_e32 v90, 0, v90
	v_max_f32_e32 v91, 0, v91
	v_pk_fma_f32 v[80:81], v[80:81], v[188:189], v[128:129] op_sel_hi:[1,0,1]
	v_pk_fma_f32 v[86:87], v[86:87], v[188:189], v[134:135] op_sel_hi:[1,0,1]
	v_pk_fma_f32 v[84:85], v[84:85], v[188:189], v[132:133] op_sel_hi:[1,0,1]
	v_pk_fma_f32 v[82:83], v[82:83], v[188:189], v[130:131] op_sel_hi:[1,0,1]
	v_max_f32_e32 v80, 0, v80
	v_max_f32_e32 v81, 0, v81
	v_max_f32_e32 v84, 0, v84
	v_max_f32_e32 v85, 0, v85
	v_max_f32_e32 v82, 0, v82
	v_max_f32_e32 v83, 0, v83
	v_pk_mul_f32 v[84:85], v[84:85], v[84:85]
	v_pk_fma_f32 v[76:77], v[76:77], v[174:175], v[140:141] op_sel_hi:[1,0,1]
	v_pk_fma_f32 v[72:73], v[72:73], v[174:175], v[136:137] op_sel_hi:[1,0,1]
	v_pk_fma_f32 v[78:79], v[78:79], v[174:175], v[142:143] op_sel_hi:[1,0,1]
	v_pk_fma_f32 v[74:75], v[74:75], v[174:175], v[138:139] op_sel_hi:[1,0,1]
	v_max_f32_e32 v76, 0, v76
	v_max_f32_e32 v72, 0, v72
	v_max_f32_e32 v77, 0, v77
	v_max_f32_e32 v73, 0, v73
	v_pk_mul_f32 v[76:77], v[76:77], v[76:77]
	v_max_f32_e32 v74, 0, v74
	v_max_f32_e32 v75, 0, v75
	v_pk_fma_f32 v[64:65], v[64:65], v[174:175], v[128:129] op_sel_hi:[1,0,1]
	v_pk_fma_f32 v[70:71], v[70:71], v[174:175], v[134:135] op_sel_hi:[1,0,1]
	v_pk_fma_f32 v[68:69], v[68:69], v[174:175], v[132:133] op_sel_hi:[1,0,1]
	v_pk_fma_f32 v[66:67], v[66:67], v[174:175], v[130:131] op_sel_hi:[1,0,1]
	v_max_f32_e32 v64, 0, v64
	v_max_f32_e32 v65, 0, v65
	v_max_f32_e32 v68, 0, v68
	v_max_f32_e32 v69, 0, v69
	v_max_f32_e32 v66, 0, v66
	v_max_f32_e32 v67, 0, v67
	v_pk_mul_f32 v[68:69], v[68:69], v[68:69]
	v_pk_add_f32 v[146:147], v[146:147], v[150:151]
	v_pk_add_f32 v[144:145], v[144:145], v[148:149]
	v_pk_add_f32 v[186:187], v[198:199], v[202:203]
	v_pk_add_f32 v[196:197], v[196:197], v[200:201]
	v_pk_add_f32 v[204:205], v[186:187], v[146:147]
	v_add_u32_e32 v186, 0x90, v178
	v_ashrrev_i32_e32 v187, 31, v186
	v_pk_add_f32 v[206:207], v[196:197], v[144:145]
	v_lshlrev_b64 v[144:145], 6, v[186:187]
	v_lshl_add_u64 v[200:201], s[12:13], 0, v[144:145]
	s_nop 0
	v_pk_add_f32 v[144:145], v[144:145], v[148:149]
	v_pk_add_f32 v[146:147], v[146:147], v[150:151]
	v_pk_add_f32 v[196:197], v[196:197], v[200:201]
	v_pk_add_f32 v[198:199], v[198:199], v[202:203]
	v_pk_add_f32 v[144:145], v[196:197], v[144:145]
	v_pk_add_f32 v[146:147], v[198:199], v[146:147]
	v_mov_b32_e32 v148, v144
	v_mov_b32_e32 v149, v206
	v_mov_b32_e32 v206, v145
	v_pk_add_f32 v[144:145], v[148:149], v[206:207]
	v_mov_b32_e32 v148, v146
	v_mov_b32_e32 v149, v204
	v_pk_add_f32 v[144:145], v[148:149], v[144:145]
	v_mov_b32_e32 v204, v147
	v_pk_add_f32 v[144:145], v[204:205], v[144:145]
	v_add_u32_e32 v196, 0xa0, v178
	v_pk_fma_f32 v[144:145], v[144:145], s[20:21], v[192:193] op_sel_hi:[1,0,0]
	v_ashrrev_i32_e32 v197, 31, v196
	v_mul_f32_e32 v146, 0x4b800000, v145
	v_cmp_gt_f32_e64 s[6:7], s68, v145
	v_cmp_gt_f32_e32 vcc, s68, v144
	s_nop 0
	v_cndmask_b32_e64 v145, v145, v146, s[6:7]
	v_rsq_f32_e32 v145, v145
	s_nop 0
	v_mul_f32_e32 v146, 0x45800000, v145
	v_cndmask_b32_e64 v194, v145, v146, s[6:7]
	v_mov_b32_e32 v194, v230
	v_mul_f32_e32 v145, 0x4b800000, v144
	v_cndmask_b32_e32 v144, v144, v145, vcc
	v_rsq_f32_e32 v144, v144
	v_pk_fma_f32 v[60:61], v[60:61], v[194:195], v[140:141] op_sel_hi:[1,0,1]
	v_pk_fma_f32 v[56:57], v[56:57], v[194:195], v[136:137] op_sel_hi:[1,0,1]
	v_pk_fma_f32 v[62:63], v[62:63], v[194:195], v[142:143] op_sel_hi:[1,0,1]
	v_mul_f32_e32 v145, 0x45800000, v144
	v_cndmask_b32_e32 v184, v144, v145, vcc
	v_mov_b32_e32 v184, v236
	v_lshlrev_b64 v[144:145], 6, v[196:197]
	v_lshl_add_u64 v[202:203], s[12:13], 0, v[144:145]
	s_nop 0
	v_pk_fma_f32 v[58:59], v[58:59], v[194:195], v[138:139] op_sel_hi:[1,0,1]
	v_max_f32_e32 v60, 0, v60
	v_max_f32_e32 v56, 0, v56
	v_max_f32_e32 v61, 0, v61
	v_max_f32_e32 v57, 0, v57
	v_pk_mul_f32 v[60:61], v[60:61], v[60:61]
	v_max_f32_e32 v58, 0, v58
	v_max_f32_e32 v59, 0, v59
	v_pk_fma_f32 v[48:49], v[48:49], v[194:195], v[128:129] op_sel_hi:[1,0,1]
	v_pk_fma_f32 v[54:55], v[54:55], v[194:195], v[134:135] op_sel_hi:[1,0,1]
	v_pk_fma_f32 v[52:53], v[52:53], v[194:195], v[132:133] op_sel_hi:[1,0,1]
	v_pk_fma_f32 v[50:51], v[50:51], v[194:195], v[130:131] op_sel_hi:[1,0,1]
	v_max_f32_e32 v48, 0, v48
	v_max_f32_e32 v49, 0, v49
	v_max_f32_e32 v52, 0, v52
	v_max_f32_e32 v53, 0, v53
	v_max_f32_e32 v50, 0, v50
	v_max_f32_e32 v51, 0, v51
	v_pk_mul_f32 v[52:53], v[52:53], v[52:53]
	v_pk_fma_f32 v[44:45], v[44:45], v[184:185], v[140:141] op_sel_hi:[1,0,1]
	v_pk_fma_f32 v[40:41], v[40:41], v[184:185], v[136:137] op_sel_hi:[1,0,1]
	v_pk_fma_f32 v[46:47], v[46:47], v[184:185], v[142:143] op_sel_hi:[1,0,1]
	v_pk_fma_f32 v[42:43], v[42:43], v[184:185], v[138:139] op_sel_hi:[1,0,1]
	v_max_f32_e32 v44, 0, v44
	v_max_f32_e32 v40, 0, v40
	v_max_f32_e32 v45, 0, v45
	v_max_f32_e32 v41, 0, v41
	v_pk_mul_f32 v[44:45], v[44:45], v[44:45]
	v_max_f32_e32 v42, 0, v42
	v_max_f32_e32 v43, 0, v43
	v_pk_fma_f32 v[32:33], v[32:33], v[184:185], v[128:129] op_sel_hi:[1,0,1]
	v_pk_fma_f32 v[38:39], v[38:39], v[184:185], v[134:135] op_sel_hi:[1,0,1]
	v_pk_fma_f32 v[36:37], v[36:37], v[184:185], v[132:133] op_sel_hi:[1,0,1]
	v_pk_fma_f32 v[34:35], v[34:35], v[184:185], v[130:131] op_sel_hi:[1,0,1]
	v_max_f32_e32 v32, 0, v32
	v_max_f32_e32 v33, 0, v33
	v_max_f32_e32 v36, 0, v36
	v_max_f32_e32 v37, 0, v37
	v_max_f32_e32 v34, 0, v34
	v_max_f32_e32 v35, 0, v35
	v_pk_mul_f32 v[36:37], v[36:37], v[36:37]
	v_pk_add_f32 v[144:145], v[144:145], v[148:149]
	v_pk_add_f32 v[146:147], v[146:147], v[150:151]
	v_pk_add_f32 v[198:199], v[198:199], v[202:203]
	v_pk_add_f32 v[200:201], v[200:201], v[204:205]
	v_pk_add_f32 v[202:203], v[198:199], v[144:145]
	v_add_u32_e32 v198, 0xb0, v178
	v_ashrrev_i32_e32 v199, 31, v198
	v_lshlrev_b64 v[144:145], 6, v[198:199]
	v_lshl_add_u64 v[208:209], s[12:13], 0, v[144:145]
	v_pk_add_f32 v[200:201], v[200:201], v[146:147]
	s_nop 0
	v_pk_add_f32 v[144:145], v[144:145], v[148:149]
	v_pk_add_f32 v[146:147], v[146:147], v[150:151]
	v_pk_add_f32 v[204:205], v[204:205], v[208:209]
	v_pk_add_f32 v[206:207], v[206:207], v[210:211]
	v_pk_add_f32 v[144:145], v[204:205], v[144:145]
	v_pk_add_f32 v[146:147], v[206:207], v[146:147]
	v_mov_b32_e32 v148, v144
	v_mov_b32_e32 v149, v202
	v_mov_b32_e32 v202, v145
	v_pk_add_f32 v[144:145], v[148:149], v[202:203]
	v_mov_b32_e32 v148, v146
	v_mov_b32_e32 v149, v200
	v_pk_add_f32 v[144:145], v[148:149], v[144:145]
	v_lshlrev_b64 v[148:149], 13, v[178:179]
	v_pk_mul_f32 v[150:151], v[122:123], v[122:123]
	v_cvt_pk_bf16_f32 v122, v124, v125
	v_cvt_pk_bf16_f32 v123, v126, v127
	v_cvt_pk_bf16_f32 v124, v120, v121
	v_lshl_add_u64 v[126:127], s[14:15], 0, v[148:149]
	v_lshlrev_b64 v[120:121], 1, v[168:169]
	v_cvt_pk_bf16_f32 v125, v150, v151
	v_lshl_add_u64 v[126:127], v[126:127], 0, v[120:121]
	global_store_dwordx4 v[126:127], v[122:125], off
	v_mov_b32_e32 v200, v147
	v_pk_add_f32 v[144:145], v[200:201], v[144:145]
	v_pk_mul_f32 v[122:123], v[112:113], v[112:113]
	v_max_f32_e32 v112, 0, v118
	v_max_f32_e32 v113, 0, v119
	v_pk_mul_f32 v[118:119], v[112:113], v[112:113]
	v_pk_mul_f32 v[124:125], v[114:115], v[114:115]
	v_cvt_pk_bf16_f32 v112, v116, v117
	v_cvt_pk_bf16_f32 v113, v118, v119
	v_cvt_pk_bf16_f32 v114, v122, v123
	v_cvt_pk_bf16_f32 v115, v124, v125
	global_store_dwordx4 v[126:127], v[112:115], off offset:256
	v_pk_mul_f32 v[116:117], v[106:107], v[106:107]
	v_pk_fma_f32 v[144:145], v[144:145], s[20:21], v[192:193] op_sel_hi:[1,0,0]
	v_lshlrev_b64 v[112:113], 13, v[172:173]
	v_pk_mul_f32 v[114:115], v[104:105], v[104:105]
	v_max_f32_e32 v104, 0, v110
	v_max_f32_e32 v105, 0, v111
	v_pk_mul_f32 v[110:111], v[104:105], v[104:105]
	v_cvt_pk_bf16_f32 v104, v108, v109
	v_lshl_add_u64 v[108:109], s[14:15], 0, v[112:113]
	v_cvt_pk_bf16_f32 v105, v110, v111
	v_cvt_pk_bf16_f32 v106, v114, v115
	v_cvt_pk_bf16_f32 v107, v116, v117
	v_lshl_add_u64 v[108:109], v[108:109], 0, v[120:121]
	global_store_dwordx4 v[108:109], v[104:107], off
	v_mul_f32_e32 v146, 0x4b800000, v145
	v_cmp_gt_f32_e64 s[6:7], s68, v145
	v_pk_mul_f32 v[104:105], v[96:97], v[96:97]
	v_max_f32_e32 v96, 0, v102
	v_max_f32_e32 v97, 0, v103
	v_pk_mul_f32 v[102:103], v[96:97], v[96:97]
	v_pk_mul_f32 v[106:107], v[98:99], v[98:99]
	v_cvt_pk_bf16_f32 v96, v100, v101
	v_cvt_pk_bf16_f32 v97, v102, v103
	v_cvt_pk_bf16_f32 v98, v104, v105
	v_cvt_pk_bf16_f32 v99, v106, v107
	global_store_dwordx4 v[108:109], v[96:99], off offset:256
	v_pk_mul_f32 v[100:101], v[90:91], v[90:91]
	v_cndmask_b32_e64 v145, v145, v146, s[6:7]
	v_lshlrev_b64 v[96:97], 13, v[180:181]
	v_pk_mul_f32 v[98:99], v[88:89], v[88:89]
	v_max_f32_e32 v88, 0, v94
	v_max_f32_e32 v89, 0, v95
	v_pk_mul_f32 v[94:95], v[88:89], v[88:89]
	v_cvt_pk_bf16_f32 v88, v92, v93
	v_lshl_add_u64 v[92:93], s[14:15], 0, v[96:97]
	v_cvt_pk_bf16_f32 v89, v94, v95
	v_cvt_pk_bf16_f32 v90, v98, v99
	v_cvt_pk_bf16_f32 v91, v100, v101
	v_lshl_add_u64 v[92:93], v[92:93], 0, v[120:121]
	global_store_dwordx4 v[92:93], v[88:91], off
	v_rsq_f32_e32 v145, v145
	v_cmp_gt_f32_e32 vcc, s68, v144
	v_pk_mul_f32 v[88:89], v[80:81], v[80:81]
	v_max_f32_e32 v80, 0, v86
	v_max_f32_e32 v81, 0, v87
	v_pk_mul_f32 v[86:87], v[80:81], v[80:81]
	v_pk_mul_f32 v[90:91], v[82:83], v[82:83]
	v_cvt_pk_bf16_f32 v80, v84, v85
	v_cvt_pk_bf16_f32 v81, v86, v87
	v_cvt_pk_bf16_f32 v82, v88, v89
	v_cvt_pk_bf16_f32 v83, v90, v91
	global_store_dwordx4 v[92:93], v[80:83], off offset:256
	v_pk_mul_f32 v[84:85], v[74:75], v[74:75]
	v_mul_f32_e32 v146, 0x45800000, v145
	v_lshlrev_b64 v[80:81], 13, v[176:177]
	v_pk_mul_f32 v[82:83], v[72:73], v[72:73]
	v_max_f32_e32 v72, 0, v78
	v_max_f32_e32 v73, 0, v79
	v_pk_mul_f32 v[78:79], v[72:73], v[72:73]
	v_cvt_pk_bf16_f32 v72, v76, v77
	v_lshl_add_u64 v[76:77], s[14:15], 0, v[80:81]
	v_cvt_pk_bf16_f32 v73, v78, v79
	v_cvt_pk_bf16_f32 v74, v82, v83
	v_cvt_pk_bf16_f32 v75, v84, v85
	v_lshl_add_u64 v[76:77], v[76:77], 0, v[120:121]
	global_store_dwordx4 v[76:77], v[72:75], off
	v_cndmask_b32_e64 v146, v145, v146, s[6:7]
	v_mov_b32_e32 v146, v240
	v_mul_f32_e32 v145, 0x4b800000, v144
	v_pk_mul_f32 v[72:73], v[64:65], v[64:65]
	v_max_f32_e32 v64, 0, v70
	v_max_f32_e32 v65, 0, v71
	v_pk_mul_f32 v[70:71], v[64:65], v[64:65]
	v_pk_mul_f32 v[74:75], v[66:67], v[66:67]
	v_cvt_pk_bf16_f32 v64, v68, v69
	v_cvt_pk_bf16_f32 v65, v70, v71
	v_cvt_pk_bf16_f32 v66, v72, v73
	v_cvt_pk_bf16_f32 v67, v74, v75
	global_store_dwordx4 v[76:77], v[64:67], off offset:256
	v_pk_mul_f32 v[68:69], v[58:59], v[58:59]
	v_cndmask_b32_e32 v144, v144, v145, vcc
	v_lshlrev_b64 v[64:65], 13, v[190:191]
	v_pk_mul_f32 v[66:67], v[56:57], v[56:57]
	v_max_f32_e32 v56, 0, v62
	v_max_f32_e32 v57, 0, v63
	v_pk_mul_f32 v[62:63], v[56:57], v[56:57]
	v_cvt_pk_bf16_f32 v56, v60, v61
	v_lshl_add_u64 v[60:61], s[14:15], 0, v[64:65]
	v_cvt_pk_bf16_f32 v57, v62, v63
	v_cvt_pk_bf16_f32 v58, v66, v67
	v_cvt_pk_bf16_f32 v59, v68, v69
	v_lshl_add_u64 v[60:61], v[60:61], 0, v[120:121]
	global_store_dwordx4 v[60:61], v[56:59], off
	v_rsq_f32_e32 v144, v144
	v_pk_fma_f32 v[28:29], v[28:29], v[146:147], v[140:141] op_sel_hi:[1,0,1]
	v_pk_mul_f32 v[56:57], v[48:49], v[48:49]
	v_max_f32_e32 v48, 0, v54
	v_max_f32_e32 v49, 0, v55
	v_pk_mul_f32 v[54:55], v[48:49], v[48:49]
	v_pk_mul_f32 v[58:59], v[50:51], v[50:51]
	v_cvt_pk_bf16_f32 v48, v52, v53
	v_cvt_pk_bf16_f32 v49, v54, v55
	v_cvt_pk_bf16_f32 v50, v56, v57
	v_cvt_pk_bf16_f32 v51, v58, v59
	global_store_dwordx4 v[60:61], v[48:51], off offset:256
	v_pk_mul_f32 v[52:53], v[42:43], v[42:43]
	v_pk_fma_f32 v[24:25], v[24:25], v[146:147], v[136:137] op_sel_hi:[1,0,1]
	v_lshlrev_b64 v[48:49], 13, v[186:187]
	v_pk_mul_f32 v[50:51], v[40:41], v[40:41]
	v_max_f32_e32 v40, 0, v46
	v_max_f32_e32 v41, 0, v47
	v_pk_mul_f32 v[46:47], v[40:41], v[40:41]
	v_cvt_pk_bf16_f32 v40, v44, v45
	v_lshl_add_u64 v[44:45], s[14:15], 0, v[48:49]
	v_cvt_pk_bf16_f32 v41, v46, v47
	v_cvt_pk_bf16_f32 v42, v50, v51
	v_cvt_pk_bf16_f32 v43, v52, v53
	v_lshl_add_u64 v[44:45], v[44:45], 0, v[120:121]
	global_store_dwordx4 v[44:45], v[40:43], off
	v_pk_fma_f32 v[30:31], v[30:31], v[146:147], v[142:143] op_sel_hi:[1,0,1]
	v_pk_fma_f32 v[26:27], v[26:27], v[146:147], v[138:139] op_sel_hi:[1,0,1]
	v_pk_mul_f32 v[40:41], v[32:33], v[32:33]
	v_max_f32_e32 v32, 0, v38
	v_max_f32_e32 v33, 0, v39
	v_pk_mul_f32 v[38:39], v[32:33], v[32:33]
	v_pk_mul_f32 v[42:43], v[34:35], v[34:35]
	v_cvt_pk_bf16_f32 v32, v36, v37
	v_cvt_pk_bf16_f32 v33, v38, v39
	v_cvt_pk_bf16_f32 v34, v40, v41
	v_cvt_pk_bf16_f32 v35, v42, v43
	v_max_f32_e32 v28, 0, v28
	v_max_f32_e32 v24, 0, v24
	v_max_f32_e32 v29, 0, v29
	v_max_f32_e32 v25, 0, v25
	global_store_dwordx4 v[44:45], v[32:35], off offset:256
	v_pk_mul_f32 v[28:29], v[28:29], v[28:29]
	v_max_f32_e32 v26, 0, v26
	v_lshlrev_b64 v[32:33], 13, v[196:197]
	v_pk_mul_f32 v[34:35], v[24:25], v[24:25]
	v_max_f32_e32 v24, 0, v30
	v_max_f32_e32 v25, 0, v31
	v_max_f32_e32 v27, 0, v27
	v_pk_mul_f32 v[30:31], v[24:25], v[24:25]
	v_pk_mul_f32 v[36:37], v[26:27], v[26:27]
	v_cvt_pk_bf16_f32 v24, v28, v29
	v_lshl_add_u64 v[28:29], s[14:15], 0, v[32:33]
	v_pk_fma_f32 v[16:17], v[16:17], v[146:147], v[128:129] op_sel_hi:[1,0,1]
	v_mul_f32_e32 v145, 0x45800000, v144
	v_cvt_pk_bf16_f32 v25, v30, v31
	v_cvt_pk_bf16_f32 v26, v34, v35
	v_cvt_pk_bf16_f32 v27, v36, v37
	v_lshl_add_u64 v[28:29], v[28:29], 0, v[120:121]
	v_pk_fma_f32 v[22:23], v[22:23], v[146:147], v[134:135] op_sel_hi:[1,0,1]
	v_pk_fma_f32 v[20:21], v[20:21], v[146:147], v[132:133] op_sel_hi:[1,0,1]
	v_pk_fma_f32 v[18:19], v[18:19], v[146:147], v[130:131] op_sel_hi:[1,0,1]
	v_max_f32_e32 v16, 0, v16
	v_max_f32_e32 v17, 0, v17
	v_cndmask_b32_e32 v144, v144, v145, vcc
	v_mov_b32_e32 v144, v244
	global_store_dwordx4 v[28:29], v[24:27], off
	v_max_f32_e32 v20, 0, v20
	v_max_f32_e32 v21, 0, v21
	v_pk_mul_f32 v[24:25], v[16:17], v[16:17]
	v_max_f32_e32 v16, 0, v22
	v_max_f32_e32 v18, 0, v18
	v_max_f32_e32 v17, 0, v23
	v_max_f32_e32 v19, 0, v19
	v_pk_mul_f32 v[20:21], v[20:21], v[20:21]
	v_pk_mul_f32 v[22:23], v[16:17], v[16:17]
	v_pk_mul_f32 v[26:27], v[18:19], v[18:19]
	v_pk_fma_f32 v[12:13], v[12:13], v[144:145], v[140:141] op_sel_hi:[1,0,1]
	v_pk_fma_f32 v[8:9], v[8:9], v[144:145], v[136:137] op_sel_hi:[1,0,1]
	v_cvt_pk_bf16_f32 v16, v20, v21
	v_cvt_pk_bf16_f32 v17, v22, v23
	v_cvt_pk_bf16_f32 v18, v24, v25
	v_cvt_pk_bf16_f32 v19, v26, v27
	v_pk_fma_f32 v[14:15], v[14:15], v[144:145], v[142:143] op_sel_hi:[1,0,1]
	v_pk_fma_f32 v[10:11], v[10:11], v[144:145], v[138:139] op_sel_hi:[1,0,1]
	v_max_f32_e32 v12, 0, v12
	v_max_f32_e32 v8, 0, v8
	v_max_f32_e32 v13, 0, v13
	v_max_f32_e32 v9, 0, v9
	global_store_dwordx4 v[28:29], v[16:19], off offset:256
	v_pk_mul_f32 v[12:13], v[12:13], v[12:13]
	v_max_f32_e32 v10, 0, v10
	v_lshlrev_b64 v[16:17], 13, v[198:199]
	v_pk_mul_f32 v[18:19], v[8:9], v[8:9]
	v_max_f32_e32 v8, 0, v14
	v_max_f32_e32 v9, 0, v15
	v_max_f32_e32 v11, 0, v11
	v_pk_mul_f32 v[14:15], v[8:9], v[8:9]
	v_pk_mul_f32 v[20:21], v[10:11], v[10:11]
	v_cvt_pk_bf16_f32 v8, v12, v13
	v_lshl_add_u64 v[12:13], s[14:15], 0, v[16:17]
	v_pk_fma_f32 v[0:1], v[0:1], v[144:145], v[128:129] op_sel_hi:[1,0,1]
	v_cvt_pk_bf16_f32 v9, v14, v15
	v_cvt_pk_bf16_f32 v10, v18, v19
	v_cvt_pk_bf16_f32 v11, v20, v21
	v_lshl_add_u64 v[12:13], v[12:13], 0, v[120:121]
	v_pk_fma_f32 v[6:7], v[6:7], v[144:145], v[134:135] op_sel_hi:[1,0,1]
	v_pk_fma_f32 v[4:5], v[4:5], v[144:145], v[132:133] op_sel_hi:[1,0,1]
	v_pk_fma_f32 v[2:3], v[2:3], v[144:145], v[130:131] op_sel_hi:[1,0,1]
	v_max_f32_e32 v0, 0, v0
	v_max_f32_e32 v1, 0, v1
	global_store_dwordx4 v[12:13], v[8:11], off
	v_max_f32_e32 v4, 0, v4
	v_max_f32_e32 v5, 0, v5
	v_pk_mul_f32 v[8:9], v[0:1], v[0:1]
	v_max_f32_e32 v0, 0, v6
	v_max_f32_e32 v2, 0, v2
	v_max_f32_e32 v1, 0, v7
	v_max_f32_e32 v3, 0, v3
	v_pk_mul_f32 v[4:5], v[4:5], v[4:5]
	v_pk_mul_f32 v[6:7], v[0:1], v[0:1]
	v_pk_mul_f32 v[10:11], v[2:3], v[2:3]
	v_cvt_pk_bf16_f32 v0, v4, v5
	v_cvt_pk_bf16_f32 v1, v6, v7
	v_cvt_pk_bf16_f32 v2, v8, v9
	v_cvt_pk_bf16_f32 v3, v10, v11
	s_mov_b64 s[6:7], -1
	s_andn2_b64 vcc, exec, s[4:5]
	global_store_dwordx4 v[12:13], v[0:3], off offset:256
	s_cbranch_vccnz .LBB0_1102
	s_andn2_b64 vcc, exec, s[10:11]
	s_cbranch_vccnz .LBB0_1101
	s_barrier
	s_branch .LBB0_1101

.LBB0_1262:
	s_lshl_b32 s27, s8, 9
	s_and_b32 s27, s27, 0xfffff000
	s_lshl_b32 s7, s8, 8
	s_addk_i32 s27, 0x5000
	s_cmpk_gt_i32 s8, 0xffdf
	s_cselect_b32 s8, s27, 0
	s_lshl_b64 s[38:39], s[8:9], 2
	s_add_u32 s38, s53, s38
	v_mov_b32_e32 v128, v175
	v_mov_b32_e32 v144, v173
	s_addc_u32 s39, s54, s39
	s_add_i32 s7, s7, s55
	s_lshl_b32 s6, s6, 8
	v_add_u32_e32 v168, s7, v144
	s_or_b32 s6, s6, s62
	v_add_u32_e32 v144, 0x4000, v168
	v_lshl_add_u32 v170, v128, 3, s6
	v_ashrrev_i32_e32 v145, 31, v144
	v_ashrrev_i32_e32 v171, 31, v170
	v_lshlrev_b64 v[144:145], 6, v[144:145]
	v_lshl_add_u64 v[132:133], v[170:171], 2, s[38:39]
	v_lshl_add_u64 v[188:189], s[14:15], 0, v[144:145]
	global_load_dwordx4 v[136:139], v[132:133], off offset:16
	global_load_dwordx4 v[140:143], v[132:133], off
	global_load_dwordx4 v[128:131], v[132:133], off offset:528
	s_nop 0
	global_load_dwordx4 v[132:135], v[132:133], off offset:512
	s_nop 0
	v_lshlrev_b32_e32 v212, 4, v175
	v_mov_b32_e32 v213, 0
	v_lshl_add_u64 v[212:213], v[212:213], 0, v[188:189]
	s_mov_b64 s[6:7], 0x2000
	v_mov_b32_e32 v248, s24
	v_lshl_add_u64 v[250:251], v[212:213], 0, s[6:7]
	global_load_dwordx4 v[214:217], v[212:213], off
	global_load_dwordx4 v[218:221], v[212:213], off offset:1024
	global_load_dwordx4 v[222:225], v[212:213], off offset:2048
	global_load_dwordx4 v[226:229], v[212:213], off offset:3072
	global_load_dwordx4 v[230:233], v[250:251], off
	global_load_dwordx4 v[236:239], v[250:251], off offset:1024
	global_load_dwordx4 v[240:243], v[250:251], off offset:2048
	global_load_dwordx4 v[244:247], v[250:251], off offset:3072
	s_nop 0
	v_ashrrev_i32_e32 v169, 31, v168
	s_waitcnt vmcnt(0)
	v_add_f32_e32 v214, v214, v215
	v_add_f32_e32 v218, v218, v219
	v_add_f32_e32 v222, v222, v223
	v_add_f32_e32 v226, v226, v227
	v_add_f32_e32 v230, v230, v231
	v_add_f32_e32 v236, v236, v237
	v_add_f32_e32 v240, v240, v241
	v_add_f32_e32 v244, v244, v245
	v_add_f32_e32 v216, v216, v217
	v_add_f32_e32 v220, v220, v221
	v_add_f32_e32 v224, v224, v225
	v_add_f32_e32 v228, v228, v229
	v_add_f32_e32 v232, v232, v233
	v_add_f32_e32 v238, v238, v239
	v_add_f32_e32 v242, v242, v243
	v_add_f32_e32 v246, v246, v247
	v_add_f32_e32 v214, v214, v216
	v_add_f32_e32 v218, v218, v220
	v_add_f32_e32 v222, v222, v224
	v_add_f32_e32 v226, v226, v228
	v_add_f32_e32 v230, v230, v232
	v_add_f32_e32 v236, v236, v238
	v_add_f32_e32 v240, v240, v242
	v_add_f32_e32 v244, v244, v246
	v_mov_b32_e32 v215, v214
	v_mov_b32_e32 v219, v218
	v_mov_b32_e32 v223, v222
	v_mov_b32_e32 v227, v226
	v_mov_b32_e32 v231, v230
	v_mov_b32_e32 v237, v236
	v_mov_b32_e32 v241, v240
	v_mov_b32_e32 v245, v244
	v_permlane16_swap_b32_e32 v214, v215
	v_permlane16_swap_b32_e32 v218, v219
	v_permlane16_swap_b32_e32 v222, v223
	v_permlane16_swap_b32_e32 v226, v227
	v_permlane16_swap_b32_e32 v230, v231
	v_permlane16_swap_b32_e32 v236, v237
	v_permlane16_swap_b32_e32 v240, v241
	v_permlane16_swap_b32_e32 v244, v245
	v_add_f32_e32 v214, v214, v215
	v_add_f32_e32 v218, v218, v219
	v_add_f32_e32 v222, v222, v223
	v_add_f32_e32 v226, v226, v227
	v_add_f32_e32 v230, v230, v231
	v_add_f32_e32 v236, v236, v237
	v_add_f32_e32 v240, v240, v241
	v_add_f32_e32 v244, v244, v245
	v_mov_b32_e32 v215, v214
	v_mov_b32_e32 v219, v218
	v_mov_b32_e32 v223, v222
	v_mov_b32_e32 v227, v226
	v_mov_b32_e32 v231, v230
	v_mov_b32_e32 v237, v236
	v_mov_b32_e32 v241, v240
	v_mov_b32_e32 v245, v244
	v_permlane32_swap_b32_e32 v214, v215
	v_permlane32_swap_b32_e32 v218, v219
	v_permlane32_swap_b32_e32 v222, v223
	v_permlane32_swap_b32_e32 v226, v227
	v_permlane32_swap_b32_e32 v230, v231
	v_permlane32_swap_b32_e32 v236, v237
	v_permlane32_swap_b32_e32 v240, v241
	v_permlane32_swap_b32_e32 v244, v245
	v_add_f32_e32 v214, v214, v215
	v_add_f32_e32 v218, v218, v219
	v_add_f32_e32 v222, v222, v223
	v_add_f32_e32 v226, v226, v227
	v_add_f32_e32 v230, v230, v231
	v_add_f32_e32 v236, v236, v237
	v_add_f32_e32 v240, v240, v241
	v_add_f32_e32 v244, v244, v245
	v_fma_f32 v214, v214, s22, v248
	v_fma_f32 v218, v218, s22, v248
	v_fma_f32 v222, v222, s22, v248
	v_fma_f32 v226, v226, s22, v248
	v_fma_f32 v230, v230, s22, v248
	v_fma_f32 v236, v236, s22, v248
	v_fma_f32 v240, v240, s22, v248
	v_fma_f32 v244, v244, s22, v248
	v_rsq_f32_e32 v214, v214
	v_rsq_f32_e32 v218, v218
	v_rsq_f32_e32 v222, v222
	v_rsq_f32_e32 v226, v226
	v_rsq_f32_e32 v230, v230
	v_rsq_f32_e32 v236, v236
	v_rsq_f32_e32 v240, v240
	v_rsq_f32_e32 v244, v244
	v_pk_add_f32 v[144:145], v[144:145], v[148:149]
	v_pk_add_f32 v[146:147], v[146:147], v[150:151]
	v_pk_add_f32 v[184:185], v[184:185], v[188:189]
	v_pk_add_f32 v[186:187], v[186:187], v[190:191]
	v_pk_add_f32 v[194:195], v[184:185], v[144:145]
	v_add_u32_e32 v144, 0x4010, v168
	v_ashrrev_i32_e32 v145, 31, v144
	v_lshlrev_b64 v[144:145], 6, v[144:145]
	v_lshl_add_u64 v[188:189], s[14:15], 0, v[144:145]
	v_pk_add_f32 v[192:193], v[186:187], v[146:147]
	s_nop 0
	v_pk_add_f32 v[144:145], v[144:145], v[148:149]
	v_pk_add_f32 v[146:147], v[146:147], v[150:151]
	v_pk_add_f32 v[184:185], v[184:185], v[188:189]
	v_pk_add_f32 v[186:187], v[186:187], v[190:191]
	v_pk_add_f32 v[144:145], v[184:185], v[144:145]
	v_pk_add_f32 v[146:147], v[186:187], v[146:147]
	v_mov_b32_e32 v148, v144
	v_mov_b32_e32 v149, v194
	v_mov_b32_e32 v194, v145
	v_pk_add_f32 v[144:145], v[148:149], v[194:195]
	v_mov_b32_e32 v148, v146
	v_mov_b32_e32 v149, v192
	v_pk_add_f32 v[144:145], v[148:149], v[144:145]
	v_mov_b32_e32 v192, v147
	v_pk_add_f32 v[144:145], v[192:193], v[144:145]
	v_mov_b64_e32 v[184:185], s[24:25]
	v_pk_fma_f32 v[144:145], v[144:145], s[22:23], v[184:185] op_sel_hi:[1,0,0]
	s_nop 0
	v_mul_f32_e32 v146, 0x4b800000, v145
	v_cmp_gt_f32_e64 s[6:7], s69, v145
	v_cmp_gt_f32_e32 vcc, s69, v144
	s_nop 0
	v_cndmask_b32_e64 v145, v145, v146, s[6:7]
	v_rsq_f32_e32 v145, v145
	s_nop 0
	v_mul_f32_e32 v146, 0x45800000, v145
	v_cndmask_b32_e64 v178, v145, v146, s[6:7]
	v_mov_b32_e32 v178, v214
	v_mul_f32_e32 v145, 0x4b800000, v144
	v_cndmask_b32_e32 v144, v144, v145, vcc
	v_rsq_f32_e32 v144, v144
	v_pk_fma_f32 v[126:127], v[126:127], v[178:179], v[142:143] op_sel_hi:[1,0,1]
	v_pk_fma_f32 v[124:125], v[124:125], v[178:179], v[140:141] op_sel_hi:[1,0,1]
	v_pk_fma_f32 v[120:121], v[120:121], v[178:179], v[136:137] op_sel_hi:[1,0,1]
	v_mul_f32_e32 v145, 0x45800000, v144
	v_cndmask_b32_e32 v172, v144, v145, vcc
	v_mov_b32_e32 v172, v218
	v_add_u32_e32 v144, 0x4020, v168
	v_ashrrev_i32_e32 v145, 31, v144
	v_lshlrev_b64 v[144:145], 6, v[144:145]
	v_lshl_add_u64 v[190:191], s[14:15], 0, v[144:145]
	s_nop 0
	v_pk_fma_f32 v[122:123], v[122:123], v[178:179], v[138:139] op_sel_hi:[1,0,1]
	v_max_f32_e32 v124, 0, v124
	v_max_f32_e32 v120, 0, v120
	v_max_f32_e32 v125, 0, v125
	v_max_f32_e32 v121, 0, v121
	v_max_f32_e32 v126, 0, v126
	v_max_f32_e32 v127, 0, v127
	v_pk_mul_f32 v[124:125], v[124:125], v[124:125]
	v_pk_mul_f32 v[120:121], v[120:121], v[120:121]
	v_max_f32_e32 v122, 0, v122
	v_max_f32_e32 v123, 0, v123
	v_pk_mul_f32 v[126:127], v[126:127], v[126:127]
	v_pk_fma_f32 v[112:113], v[112:113], v[178:179], v[128:129] op_sel_hi:[1,0,1]
	v_pk_fma_f32 v[118:119], v[118:119], v[178:179], v[134:135] op_sel_hi:[1,0,1]
	v_pk_fma_f32 v[116:117], v[116:117], v[178:179], v[132:133] op_sel_hi:[1,0,1]
	v_pk_fma_f32 v[114:115], v[114:115], v[178:179], v[130:131] op_sel_hi:[1,0,1]
	v_max_f32_e32 v112, 0, v112
	v_max_f32_e32 v113, 0, v113
	v_max_f32_e32 v116, 0, v116
	v_max_f32_e32 v117, 0, v117
	v_max_f32_e32 v114, 0, v114
	v_max_f32_e32 v115, 0, v115
	v_pk_mul_f32 v[116:117], v[116:117], v[116:117]
	v_pk_fma_f32 v[108:109], v[108:109], v[172:173], v[140:141] op_sel_hi:[1,0,1]
	v_pk_fma_f32 v[104:105], v[104:105], v[172:173], v[136:137] op_sel_hi:[1,0,1]
	v_pk_fma_f32 v[110:111], v[110:111], v[172:173], v[142:143] op_sel_hi:[1,0,1]
	v_pk_fma_f32 v[106:107], v[106:107], v[172:173], v[138:139] op_sel_hi:[1,0,1]
	v_max_f32_e32 v108, 0, v108
	v_max_f32_e32 v104, 0, v104
	v_max_f32_e32 v109, 0, v109
	v_max_f32_e32 v105, 0, v105
	v_pk_mul_f32 v[108:109], v[108:109], v[108:109]
	v_max_f32_e32 v106, 0, v106
	v_max_f32_e32 v107, 0, v107
	v_pk_fma_f32 v[96:97], v[96:97], v[172:173], v[128:129] op_sel_hi:[1,0,1]
	v_pk_fma_f32 v[102:103], v[102:103], v[172:173], v[134:135] op_sel_hi:[1,0,1]
	v_pk_fma_f32 v[100:101], v[100:101], v[172:173], v[132:133] op_sel_hi:[1,0,1]
	v_pk_fma_f32 v[98:99], v[98:99], v[172:173], v[130:131] op_sel_hi:[1,0,1]
	v_max_f32_e32 v96, 0, v96
	v_max_f32_e32 v97, 0, v97
	v_max_f32_e32 v100, 0, v100
	v_max_f32_e32 v101, 0, v101
	v_max_f32_e32 v98, 0, v98
	v_max_f32_e32 v99, 0, v99
	v_pk_mul_f32 v[100:101], v[100:101], v[100:101]
	v_pk_add_f32 v[144:145], v[144:145], v[148:149]
	v_pk_add_f32 v[146:147], v[146:147], v[150:151]
	v_pk_add_f32 v[186:187], v[186:187], v[190:191]
	v_pk_add_f32 v[188:189], v[188:189], v[192:193]
	v_pk_add_f32 v[196:197], v[186:187], v[144:145]
	v_add_u32_e32 v144, 0x4030, v168
	v_ashrrev_i32_e32 v145, 31, v144
	v_lshlrev_b64 v[144:145], 6, v[144:145]
	v_lshl_add_u64 v[190:191], s[14:15], 0, v[144:145]
	v_pk_add_f32 v[194:195], v[188:189], v[146:147]
	s_nop 0
	v_pk_add_f32 v[144:145], v[144:145], v[148:149]
	v_pk_add_f32 v[146:147], v[146:147], v[150:151]
	v_pk_add_f32 v[186:187], v[186:187], v[190:191]
	v_pk_add_f32 v[188:189], v[188:189], v[192:193]
	v_pk_add_f32 v[144:145], v[186:187], v[144:145]
	v_pk_add_f32 v[146:147], v[188:189], v[146:147]
	v_mov_b32_e32 v148, v144
	v_mov_b32_e32 v149, v196
	v_mov_b32_e32 v196, v145
	v_pk_add_f32 v[144:145], v[148:149], v[196:197]
	v_mov_b32_e32 v148, v146
	v_mov_b32_e32 v149, v194
	v_pk_add_f32 v[144:145], v[148:149], v[144:145]
	v_mov_b32_e32 v194, v147
	v_pk_add_f32 v[144:145], v[194:195], v[144:145]
	s_nop 0
	v_pk_fma_f32 v[144:145], v[144:145], s[22:23], v[184:185] op_sel_hi:[1,0,0]
	s_nop 0
	v_mul_f32_e32 v146, 0x4b800000, v145
	v_cmp_gt_f32_e64 s[6:7], s69, v145
	v_cmp_gt_f32_e32 vcc, s69, v144
	s_nop 0
	v_cndmask_b32_e64 v145, v145, v146, s[6:7]
	v_rsq_f32_e32 v145, v145
	s_nop 0
	v_mul_f32_e32 v146, 0x45800000, v145
	v_cndmask_b32_e64 v180, v145, v146, s[6:7]
	v_mov_b32_e32 v180, v222
	v_mul_f32_e32 v145, 0x4b800000, v144
	v_cndmask_b32_e32 v144, v144, v145, vcc
	v_rsq_f32_e32 v144, v144
	v_pk_fma_f32 v[92:93], v[92:93], v[180:181], v[140:141] op_sel_hi:[1,0,1]
	v_pk_fma_f32 v[88:89], v[88:89], v[180:181], v[136:137] op_sel_hi:[1,0,1]
	v_pk_fma_f32 v[94:95], v[94:95], v[180:181], v[142:143] op_sel_hi:[1,0,1]
	v_mul_f32_e32 v145, 0x45800000, v144
	v_cndmask_b32_e32 v174, v144, v145, vcc
	v_mov_b32_e32 v174, v226
	v_add_u32_e32 v144, 0x4080, v168
	v_ashrrev_i32_e32 v145, 31, v144
	v_lshlrev_b64 v[144:145], 6, v[144:145]
	v_lshl_add_u64 v[190:191], s[14:15], 0, v[144:145]
	s_nop 0
	v_pk_fma_f32 v[90:91], v[90:91], v[180:181], v[138:139] op_sel_hi:[1,0,1]
	v_max_f32_e32 v92, 0, v92
	v_max_f32_e32 v88, 0, v88
	v_max_f32_e32 v93, 0, v93
	v_max_f32_e32 v89, 0, v89
	v_pk_mul_f32 v[92:93], v[92:93], v[92:93]
	v_max_f32_e32 v90, 0, v90
	v_max_f32_e32 v91, 0, v91
	v_pk_fma_f32 v[80:81], v[80:81], v[180:181], v[128:129] op_sel_hi:[1,0,1]
	v_pk_fma_f32 v[86:87], v[86:87], v[180:181], v[134:135] op_sel_hi:[1,0,1]
	v_pk_fma_f32 v[84:85], v[84:85], v[180:181], v[132:133] op_sel_hi:[1,0,1]
	v_pk_fma_f32 v[82:83], v[82:83], v[180:181], v[130:131] op_sel_hi:[1,0,1]
	v_max_f32_e32 v80, 0, v80
	v_max_f32_e32 v81, 0, v81
	v_max_f32_e32 v84, 0, v84
	v_max_f32_e32 v85, 0, v85
	v_max_f32_e32 v82, 0, v82
	v_max_f32_e32 v83, 0, v83
	v_pk_mul_f32 v[84:85], v[84:85], v[84:85]
	v_pk_fma_f32 v[76:77], v[76:77], v[174:175], v[140:141] op_sel_hi:[1,0,1]
	v_pk_fma_f32 v[72:73], v[72:73], v[174:175], v[136:137] op_sel_hi:[1,0,1]
	v_pk_fma_f32 v[78:79], v[78:79], v[174:175], v[142:143] op_sel_hi:[1,0,1]
	v_pk_fma_f32 v[74:75], v[74:75], v[174:175], v[138:139] op_sel_hi:[1,0,1]
	v_max_f32_e32 v76, 0, v76
	v_max_f32_e32 v72, 0, v72
	v_max_f32_e32 v77, 0, v77
	v_max_f32_e32 v73, 0, v73
	v_pk_mul_f32 v[76:77], v[76:77], v[76:77]
	v_max_f32_e32 v74, 0, v74
	v_max_f32_e32 v75, 0, v75
	v_pk_fma_f32 v[64:65], v[64:65], v[174:175], v[128:129] op_sel_hi:[1,0,1]
	v_pk_fma_f32 v[70:71], v[70:71], v[174:175], v[134:135] op_sel_hi:[1,0,1]
	v_pk_fma_f32 v[68:69], v[68:69], v[174:175], v[132:133] op_sel_hi:[1,0,1]
	v_pk_fma_f32 v[66:67], v[66:67], v[174:175], v[130:131] op_sel_hi:[1,0,1]
	v_max_f32_e32 v64, 0, v64
	v_max_f32_e32 v65, 0, v65
	v_max_f32_e32 v68, 0, v68
	v_max_f32_e32 v69, 0, v69
	v_max_f32_e32 v66, 0, v66
	v_max_f32_e32 v67, 0, v67
	v_pk_mul_f32 v[68:69], v[68:69], v[68:69]
	v_pk_add_f32 v[144:145], v[144:145], v[148:149]
	v_pk_add_f32 v[146:147], v[146:147], v[150:151]
	v_pk_add_f32 v[186:187], v[186:187], v[190:191]
	v_pk_add_f32 v[188:189], v[188:189], v[192:193]
	v_pk_add_f32 v[196:197], v[186:187], v[144:145]
	v_add_u32_e32 v144, 0x4090, v168
	v_ashrrev_i32_e32 v145, 31, v144
	v_lshlrev_b64 v[144:145], 6, v[144:145]
	v_lshl_add_u64 v[190:191], s[14:15], 0, v[144:145]
	v_pk_add_f32 v[194:195], v[188:189], v[146:147]
	s_nop 0
	v_pk_add_f32 v[144:145], v[144:145], v[148:149]
	v_pk_add_f32 v[146:147], v[146:147], v[150:151]
	v_pk_add_f32 v[186:187], v[186:187], v[190:191]
	v_pk_add_f32 v[188:189], v[188:189], v[192:193]
	v_pk_add_f32 v[144:145], v[186:187], v[144:145]
	v_pk_add_f32 v[146:147], v[188:189], v[146:147]
	v_mov_b32_e32 v148, v144
	v_mov_b32_e32 v149, v196
	v_mov_b32_e32 v196, v145
	v_pk_add_f32 v[144:145], v[148:149], v[196:197]
	v_mov_b32_e32 v148, v146
	v_mov_b32_e32 v149, v194
	v_pk_add_f32 v[144:145], v[148:149], v[144:145]
	v_mov_b32_e32 v194, v147
	v_pk_add_f32 v[144:145], v[194:195], v[144:145]
	s_nop 0
	v_pk_fma_f32 v[144:145], v[144:145], s[22:23], v[184:185] op_sel_hi:[1,0,0]
	s_nop 0
	v_mul_f32_e32 v146, 0x4b800000, v145
	v_cmp_gt_f32_e64 s[6:7], s69, v145
	v_cmp_gt_f32_e32 vcc, s69, v144
	s_nop 0
	v_cndmask_b32_e64 v145, v145, v146, s[6:7]
	v_rsq_f32_e32 v145, v145
	s_nop 0
	v_mul_f32_e32 v146, 0x45800000, v145
	v_cndmask_b32_e64 v182, v145, v146, s[6:7]
	v_mov_b32_e32 v182, v230
	v_mul_f32_e32 v145, 0x4b800000, v144
	v_cndmask_b32_e32 v144, v144, v145, vcc
	v_rsq_f32_e32 v144, v144
	v_pk_fma_f32 v[60:61], v[60:61], v[182:183], v[140:141] op_sel_hi:[1,0,1]
	v_pk_fma_f32 v[56:57], v[56:57], v[182:183], v[136:137] op_sel_hi:[1,0,1]
	v_pk_fma_f32 v[62:63], v[62:63], v[182:183], v[142:143] op_sel_hi:[1,0,1]
	v_mul_f32_e32 v145, 0x45800000, v144
	v_cndmask_b32_e32 v176, v144, v145, vcc
	v_mov_b32_e32 v176, v236
	v_add_u32_e32 v144, 0x40a0, v168
	v_ashrrev_i32_e32 v145, 31, v144
	v_lshlrev_b64 v[144:145], 6, v[144:145]
	v_lshl_add_u64 v[190:191], s[14:15], 0, v[144:145]
	s_nop 0
	v_pk_fma_f32 v[58:59], v[58:59], v[182:183], v[138:139] op_sel_hi:[1,0,1]
	v_max_f32_e32 v60, 0, v60
	v_max_f32_e32 v56, 0, v56
	v_max_f32_e32 v61, 0, v61
	v_max_f32_e32 v57, 0, v57
	v_pk_mul_f32 v[60:61], v[60:61], v[60:61]
	v_max_f32_e32 v58, 0, v58
	v_max_f32_e32 v59, 0, v59
	v_pk_fma_f32 v[48:49], v[48:49], v[182:183], v[128:129] op_sel_hi:[1,0,1]
	v_pk_fma_f32 v[54:55], v[54:55], v[182:183], v[134:135] op_sel_hi:[1,0,1]
	v_pk_fma_f32 v[52:53], v[52:53], v[182:183], v[132:133] op_sel_hi:[1,0,1]
	v_pk_fma_f32 v[50:51], v[50:51], v[182:183], v[130:131] op_sel_hi:[1,0,1]
	v_max_f32_e32 v48, 0, v48
	v_max_f32_e32 v49, 0, v49
	v_max_f32_e32 v52, 0, v52
	v_max_f32_e32 v53, 0, v53
	v_max_f32_e32 v50, 0, v50
	v_max_f32_e32 v51, 0, v51
	v_pk_mul_f32 v[52:53], v[52:53], v[52:53]
	v_pk_fma_f32 v[44:45], v[44:45], v[176:177], v[140:141] op_sel_hi:[1,0,1]
	v_pk_fma_f32 v[40:41], v[40:41], v[176:177], v[136:137] op_sel_hi:[1,0,1]
	v_pk_fma_f32 v[46:47], v[46:47], v[176:177], v[142:143] op_sel_hi:[1,0,1]
	v_pk_fma_f32 v[42:43], v[42:43], v[176:177], v[138:139] op_sel_hi:[1,0,1]
	v_max_f32_e32 v44, 0, v44
	v_max_f32_e32 v40, 0, v40
	v_max_f32_e32 v45, 0, v45
	v_max_f32_e32 v41, 0, v41
	v_pk_mul_f32 v[44:45], v[44:45], v[44:45]
	v_max_f32_e32 v42, 0, v42
	v_max_f32_e32 v43, 0, v43
	v_pk_fma_f32 v[32:33], v[32:33], v[176:177], v[128:129] op_sel_hi:[1,0,1]
	v_pk_fma_f32 v[38:39], v[38:39], v[176:177], v[134:135] op_sel_hi:[1,0,1]
	v_pk_fma_f32 v[36:37], v[36:37], v[176:177], v[132:133] op_sel_hi:[1,0,1]
	v_pk_fma_f32 v[34:35], v[34:35], v[176:177], v[130:131] op_sel_hi:[1,0,1]
	v_max_f32_e32 v32, 0, v32
	v_max_f32_e32 v33, 0, v33
	v_max_f32_e32 v36, 0, v36
	v_max_f32_e32 v37, 0, v37
	v_max_f32_e32 v34, 0, v34
	v_max_f32_e32 v35, 0, v35
	v_pk_mul_f32 v[36:37], v[36:37], v[36:37]
	v_pk_add_f32 v[146:147], v[146:147], v[150:151]
	v_pk_add_f32 v[144:145], v[144:145], v[148:149]
	v_pk_add_f32 v[188:189], v[188:189], v[192:193]
	v_pk_add_f32 v[190:191], v[186:187], v[190:191]
	v_pk_add_f32 v[186:187], v[188:189], v[146:147]
	v_pk_add_f32 v[188:189], v[190:191], v[144:145]
	v_add_u32_e32 v144, 0x40b0, v168
	v_ashrrev_i32_e32 v145, 31, v144
	v_lshlrev_b64 v[144:145], 6, v[144:145]
	v_lshl_add_u64 v[194:195], s[14:15], 0, v[144:145]
	s_nop 0
	v_pk_add_f32 v[144:145], v[144:145], v[148:149]
	v_pk_add_f32 v[146:147], v[146:147], v[150:151]
	v_pk_add_f32 v[190:191], v[190:191], v[194:195]
	v_pk_add_f32 v[192:193], v[192:193], v[196:197]
	v_pk_add_f32 v[144:145], v[190:191], v[144:145]
	v_pk_add_f32 v[146:147], v[192:193], v[146:147]
	v_mov_b32_e32 v148, v144
	v_mov_b32_e32 v149, v188
	v_mov_b32_e32 v188, v145
	v_pk_add_f32 v[144:145], v[148:149], v[188:189]
	v_mov_b32_e32 v148, v146
	v_mov_b32_e32 v149, v186
	v_pk_add_f32 v[144:145], v[148:149], v[144:145]
	v_lshlrev_b64 v[148:149], 13, v[168:169]
	v_pk_mul_f32 v[150:151], v[122:123], v[122:123]
	v_cvt_pk_bf16_f32 v122, v124, v125
	v_cvt_pk_bf16_f32 v123, v126, v127
	v_cvt_pk_bf16_f32 v124, v120, v121
	v_lshl_add_u64 v[126:127], s[16:17], 0, v[148:149]
	v_lshlrev_b64 v[120:121], 1, v[170:171]
	v_cvt_pk_bf16_f32 v125, v150, v151
	v_lshl_add_u64 v[126:127], v[126:127], 0, v[120:121]
	global_store_dwordx4 v[126:127], v[122:125], off
	v_mov_b32_e32 v186, v147
	v_pk_add_f32 v[144:145], v[186:187], v[144:145]
	v_pk_mul_f32 v[122:123], v[112:113], v[112:113]
	v_max_f32_e32 v112, 0, v118
	v_max_f32_e32 v113, 0, v119
	v_pk_mul_f32 v[118:119], v[112:113], v[112:113]
	v_pk_mul_f32 v[124:125], v[114:115], v[114:115]
	v_cvt_pk_bf16_f32 v112, v116, v117
	v_cvt_pk_bf16_f32 v113, v118, v119
	v_cvt_pk_bf16_f32 v114, v122, v123
	v_cvt_pk_bf16_f32 v115, v124, v125
	global_store_dwordx4 v[126:127], v[112:115], off offset:256
	v_pk_mul_f32 v[116:117], v[106:107], v[106:107]
	v_pk_fma_f32 v[144:145], v[144:145], s[22:23], v[184:185] op_sel_hi:[1,0,0]
	v_add_u32_e32 v112, 16, v168
	v_ashrrev_i32_e32 v113, 31, v112
	v_lshlrev_b64 v[112:113], 13, v[112:113]
	v_pk_mul_f32 v[114:115], v[104:105], v[104:105]
	v_max_f32_e32 v104, 0, v110
	v_max_f32_e32 v105, 0, v111
	v_pk_mul_f32 v[110:111], v[104:105], v[104:105]
	v_cvt_pk_bf16_f32 v104, v108, v109
	v_lshl_add_u64 v[108:109], s[16:17], 0, v[112:113]
	v_cvt_pk_bf16_f32 v105, v110, v111
	v_cvt_pk_bf16_f32 v106, v114, v115
	v_cvt_pk_bf16_f32 v107, v116, v117
	v_lshl_add_u64 v[108:109], v[108:109], 0, v[120:121]
	global_store_dwordx4 v[108:109], v[104:107], off
	v_mul_f32_e32 v146, 0x4b800000, v145
	v_cmp_gt_f32_e64 s[6:7], s69, v145
	v_pk_mul_f32 v[104:105], v[96:97], v[96:97]
	v_max_f32_e32 v96, 0, v102
	v_max_f32_e32 v97, 0, v103
	v_pk_mul_f32 v[102:103], v[96:97], v[96:97]
	v_pk_mul_f32 v[106:107], v[98:99], v[98:99]
	v_cvt_pk_bf16_f32 v96, v100, v101
	v_cvt_pk_bf16_f32 v97, v102, v103
	v_cvt_pk_bf16_f32 v98, v104, v105
	v_cvt_pk_bf16_f32 v99, v106, v107
	global_store_dwordx4 v[108:109], v[96:99], off offset:256
	v_pk_mul_f32 v[100:101], v[90:91], v[90:91]
	v_cndmask_b32_e64 v145, v145, v146, s[6:7]
	v_add_u32_e32 v96, 32, v168
	v_ashrrev_i32_e32 v97, 31, v96
	v_lshlrev_b64 v[96:97], 13, v[96:97]
	v_pk_mul_f32 v[98:99], v[88:89], v[88:89]
	v_max_f32_e32 v88, 0, v94
	v_max_f32_e32 v89, 0, v95
	v_pk_mul_f32 v[94:95], v[88:89], v[88:89]
	v_cvt_pk_bf16_f32 v88, v92, v93
	v_lshl_add_u64 v[92:93], s[16:17], 0, v[96:97]
	v_cvt_pk_bf16_f32 v89, v94, v95
	v_cvt_pk_bf16_f32 v90, v98, v99
	v_cvt_pk_bf16_f32 v91, v100, v101
	v_lshl_add_u64 v[92:93], v[92:93], 0, v[120:121]
	global_store_dwordx4 v[92:93], v[88:91], off
	v_rsq_f32_e32 v145, v145
	v_cmp_gt_f32_e32 vcc, s69, v144
	v_pk_mul_f32 v[88:89], v[80:81], v[80:81]
	v_max_f32_e32 v80, 0, v86
	v_max_f32_e32 v81, 0, v87
	v_pk_mul_f32 v[86:87], v[80:81], v[80:81]
	v_pk_mul_f32 v[90:91], v[82:83], v[82:83]
	v_cvt_pk_bf16_f32 v80, v84, v85
	v_cvt_pk_bf16_f32 v81, v86, v87
	v_cvt_pk_bf16_f32 v82, v88, v89
	v_cvt_pk_bf16_f32 v83, v90, v91
	global_store_dwordx4 v[92:93], v[80:83], off offset:256
	v_pk_mul_f32 v[84:85], v[74:75], v[74:75]
	v_mul_f32_e32 v146, 0x45800000, v145
	v_add_u32_e32 v80, 48, v168
	v_ashrrev_i32_e32 v81, 31, v80
	v_lshlrev_b64 v[80:81], 13, v[80:81]
	v_pk_mul_f32 v[82:83], v[72:73], v[72:73]
	v_max_f32_e32 v72, 0, v78
	v_max_f32_e32 v73, 0, v79
	v_pk_mul_f32 v[78:79], v[72:73], v[72:73]
	v_cvt_pk_bf16_f32 v72, v76, v77
	v_lshl_add_u64 v[76:77], s[16:17], 0, v[80:81]
	v_cvt_pk_bf16_f32 v73, v78, v79
	v_cvt_pk_bf16_f32 v74, v82, v83
	v_cvt_pk_bf16_f32 v75, v84, v85
	v_lshl_add_u64 v[76:77], v[76:77], 0, v[120:121]
	global_store_dwordx4 v[76:77], v[72:75], off
	v_cndmask_b32_e64 v146, v145, v146, s[6:7]
	v_mov_b32_e32 v146, v240
	v_mul_f32_e32 v145, 0x4b800000, v144
	v_pk_mul_f32 v[72:73], v[64:65], v[64:65]
	v_max_f32_e32 v64, 0, v70
	v_max_f32_e32 v65, 0, v71
	v_pk_mul_f32 v[70:71], v[64:65], v[64:65]
	v_pk_mul_f32 v[74:75], v[66:67], v[66:67]
	v_cvt_pk_bf16_f32 v64, v68, v69
	v_cvt_pk_bf16_f32 v65, v70, v71
	v_cvt_pk_bf16_f32 v66, v72, v73
	v_cvt_pk_bf16_f32 v67, v74, v75
	global_store_dwordx4 v[76:77], v[64:67], off offset:256
	v_pk_mul_f32 v[68:69], v[58:59], v[58:59]
	v_pk_fma_f32 v[28:29], v[28:29], v[146:147], v[140:141] op_sel_hi:[1,0,1]
	v_add_u32_e32 v64, 0x80, v168
	v_ashrrev_i32_e32 v65, 31, v64
	v_lshlrev_b64 v[64:65], 13, v[64:65]
	v_pk_mul_f32 v[66:67], v[56:57], v[56:57]
	v_max_f32_e32 v56, 0, v62
	v_max_f32_e32 v57, 0, v63
	v_pk_mul_f32 v[62:63], v[56:57], v[56:57]
	v_cvt_pk_bf16_f32 v56, v60, v61
	v_lshl_add_u64 v[60:61], s[16:17], 0, v[64:65]
	v_cvt_pk_bf16_f32 v57, v62, v63
	v_cvt_pk_bf16_f32 v58, v66, v67
	v_cvt_pk_bf16_f32 v59, v68, v69
	v_lshl_add_u64 v[60:61], v[60:61], 0, v[120:121]
	global_store_dwordx4 v[60:61], v[56:59], off
	v_pk_fma_f32 v[24:25], v[24:25], v[146:147], v[136:137] op_sel_hi:[1,0,1]
	v_cndmask_b32_e32 v144, v144, v145, vcc
	v_pk_mul_f32 v[56:57], v[48:49], v[48:49]
	v_max_f32_e32 v48, 0, v54
	v_max_f32_e32 v49, 0, v55
	v_pk_mul_f32 v[54:55], v[48:49], v[48:49]
	v_pk_mul_f32 v[58:59], v[50:51], v[50:51]
	v_cvt_pk_bf16_f32 v48, v52, v53
	v_cvt_pk_bf16_f32 v49, v54, v55
	v_cvt_pk_bf16_f32 v50, v56, v57
	v_cvt_pk_bf16_f32 v51, v58, v59
	global_store_dwordx4 v[60:61], v[48:51], off offset:256
	v_pk_mul_f32 v[52:53], v[42:43], v[42:43]
	v_pk_fma_f32 v[30:31], v[30:31], v[146:147], v[142:143] op_sel_hi:[1,0,1]
	v_add_u32_e32 v48, 0x90, v168
	v_ashrrev_i32_e32 v49, 31, v48
	v_lshlrev_b64 v[48:49], 13, v[48:49]
	v_pk_mul_f32 v[50:51], v[40:41], v[40:41]
	v_max_f32_e32 v40, 0, v46
	v_max_f32_e32 v41, 0, v47
	v_pk_mul_f32 v[46:47], v[40:41], v[40:41]
	v_cvt_pk_bf16_f32 v40, v44, v45
	v_lshl_add_u64 v[44:45], s[16:17], 0, v[48:49]
	v_cvt_pk_bf16_f32 v41, v46, v47
	v_cvt_pk_bf16_f32 v42, v50, v51
	v_cvt_pk_bf16_f32 v43, v52, v53
	v_lshl_add_u64 v[44:45], v[44:45], 0, v[120:121]
	global_store_dwordx4 v[44:45], v[40:43], off
	v_pk_fma_f32 v[26:27], v[26:27], v[146:147], v[138:139] op_sel_hi:[1,0,1]
	v_max_f32_e32 v28, 0, v28
	v_pk_mul_f32 v[40:41], v[32:33], v[32:33]
	v_max_f32_e32 v32, 0, v38
	v_max_f32_e32 v33, 0, v39
	v_pk_mul_f32 v[38:39], v[32:33], v[32:33]
	v_pk_mul_f32 v[42:43], v[34:35], v[34:35]
	v_cvt_pk_bf16_f32 v32, v36, v37
	v_cvt_pk_bf16_f32 v33, v38, v39
	v_cvt_pk_bf16_f32 v34, v40, v41
	v_cvt_pk_bf16_f32 v35, v42, v43
	global_store_dwordx4 v[44:45], v[32:35], off offset:256
	v_max_f32_e32 v24, 0, v24
	v_max_f32_e32 v29, 0, v29
	v_add_u32_e32 v32, 0xa0, v168
	v_ashrrev_i32_e32 v33, 31, v32
	v_max_f32_e32 v25, 0, v25
	v_rsq_f32_e32 v144, v144
	v_lshlrev_b64 v[32:33], 13, v[32:33]
	v_pk_mul_f32 v[28:29], v[28:29], v[28:29]
	v_pk_mul_f32 v[34:35], v[24:25], v[24:25]
	v_max_f32_e32 v24, 0, v30
	v_max_f32_e32 v26, 0, v26
	v_max_f32_e32 v25, 0, v31
	v_max_f32_e32 v27, 0, v27
	v_pk_mul_f32 v[30:31], v[24:25], v[24:25]
	v_pk_mul_f32 v[36:37], v[26:27], v[26:27]
	v_cvt_pk_bf16_f32 v24, v28, v29
	v_lshl_add_u64 v[28:29], s[16:17], 0, v[32:33]
	v_pk_fma_f32 v[16:17], v[16:17], v[146:147], v[128:129] op_sel_hi:[1,0,1]
	v_cvt_pk_bf16_f32 v25, v30, v31
	v_cvt_pk_bf16_f32 v26, v34, v35
	v_cvt_pk_bf16_f32 v27, v36, v37
	v_lshl_add_u64 v[28:29], v[28:29], 0, v[120:121]
	v_pk_fma_f32 v[22:23], v[22:23], v[146:147], v[134:135] op_sel_hi:[1,0,1]
	v_pk_fma_f32 v[20:21], v[20:21], v[146:147], v[132:133] op_sel_hi:[1,0,1]
	v_pk_fma_f32 v[18:19], v[18:19], v[146:147], v[130:131] op_sel_hi:[1,0,1]
	v_max_f32_e32 v16, 0, v16
	v_max_f32_e32 v17, 0, v17
	global_store_dwordx4 v[28:29], v[24:27], off
	v_max_f32_e32 v20, 0, v20
	v_max_f32_e32 v21, 0, v21
	v_pk_mul_f32 v[24:25], v[16:17], v[16:17]
	v_max_f32_e32 v16, 0, v22
	v_max_f32_e32 v18, 0, v18
	v_max_f32_e32 v17, 0, v23
	v_max_f32_e32 v19, 0, v19
	v_mul_f32_e32 v145, 0x45800000, v144
	v_pk_mul_f32 v[20:21], v[20:21], v[20:21]
	v_pk_mul_f32 v[22:23], v[16:17], v[16:17]
	v_pk_mul_f32 v[26:27], v[18:19], v[18:19]
	v_cndmask_b32_e32 v144, v144, v145, vcc
	v_mov_b32_e32 v144, v244
	v_cvt_pk_bf16_f32 v16, v20, v21
	v_cvt_pk_bf16_f32 v17, v22, v23
	v_cvt_pk_bf16_f32 v18, v24, v25
	v_cvt_pk_bf16_f32 v19, v26, v27
	global_store_dwordx4 v[28:29], v[16:19], off offset:256
	v_pk_fma_f32 v[12:13], v[12:13], v[144:145], v[140:141] op_sel_hi:[1,0,1]
	v_pk_fma_f32 v[8:9], v[8:9], v[144:145], v[136:137] op_sel_hi:[1,0,1]
	v_add_u32_e32 v16, 0xb0, v168
	v_ashrrev_i32_e32 v17, 31, v16
	v_pk_fma_f32 v[14:15], v[14:15], v[144:145], v[142:143] op_sel_hi:[1,0,1]
	v_pk_fma_f32 v[10:11], v[10:11], v[144:145], v[138:139] op_sel_hi:[1,0,1]
	v_max_f32_e32 v12, 0, v12
	v_max_f32_e32 v8, 0, v8
	v_max_f32_e32 v13, 0, v13
	v_max_f32_e32 v9, 0, v9
	v_lshlrev_b64 v[16:17], 13, v[16:17]
	v_pk_mul_f32 v[12:13], v[12:13], v[12:13]
	v_pk_mul_f32 v[18:19], v[8:9], v[8:9]
	v_max_f32_e32 v8, 0, v14
	v_max_f32_e32 v10, 0, v10
	v_max_f32_e32 v9, 0, v15
	v_max_f32_e32 v11, 0, v11
	v_pk_mul_f32 v[14:15], v[8:9], v[8:9]
	v_pk_mul_f32 v[20:21], v[10:11], v[10:11]
	v_cvt_pk_bf16_f32 v8, v12, v13
	v_lshl_add_u64 v[12:13], s[16:17], 0, v[16:17]
	v_pk_fma_f32 v[0:1], v[0:1], v[144:145], v[128:129] op_sel_hi:[1,0,1]
	v_cvt_pk_bf16_f32 v9, v14, v15
	v_cvt_pk_bf16_f32 v10, v18, v19
	v_cvt_pk_bf16_f32 v11, v20, v21
	v_lshl_add_u64 v[12:13], v[12:13], 0, v[120:121]
	v_pk_fma_f32 v[6:7], v[6:7], v[144:145], v[134:135] op_sel_hi:[1,0,1]
	v_pk_fma_f32 v[4:5], v[4:5], v[144:145], v[132:133] op_sel_hi:[1,0,1]
	v_pk_fma_f32 v[2:3], v[2:3], v[144:145], v[130:131] op_sel_hi:[1,0,1]
	v_max_f32_e32 v0, 0, v0
	v_max_f32_e32 v1, 0, v1
	global_store_dwordx4 v[12:13], v[8:11], off
	v_max_f32_e32 v4, 0, v4
	v_max_f32_e32 v5, 0, v5
	v_pk_mul_f32 v[8:9], v[0:1], v[0:1]
	v_max_f32_e32 v0, 0, v6
	v_max_f32_e32 v2, 0, v2
	v_max_f32_e32 v1, 0, v7
	v_max_f32_e32 v3, 0, v3
	v_pk_mul_f32 v[4:5], v[4:5], v[4:5]
	v_pk_mul_f32 v[6:7], v[0:1], v[0:1]
	v_pk_mul_f32 v[10:11], v[2:3], v[2:3]
	v_cvt_pk_bf16_f32 v0, v4, v5
	v_cvt_pk_bf16_f32 v1, v6, v7
	v_cvt_pk_bf16_f32 v2, v8, v9
	v_cvt_pk_bf16_f32 v3, v10, v11
	s_mov_b64 s[6:7], -1
	s_andn2_b64 vcc, exec, s[4:5]
	global_store_dwordx4 v[12:13], v[0:3], off offset:256
	s_cbranch_vccnz .LBB0_1255
	s_andn2_b64 vcc, exec, s[10:11]
	s_cbranch_vccnz .LBB0_1254
	s_barrier
	s_branch .LBB0_1254
